# v36: v32 + loop-edge rotation in the diff and GQA attention loops (next iteration's LDS fragment addresses computed before the loop-back barrier)
# speedup vs baseline: 1.0042x; 1.0042x over previous
.Lgq_rot:
	ds_read_b128 v[210:213], v248
	ds_read_b128 v[214:217], v248 offset:32
	ds_read_b128 v[218:221], v248 offset:64
	ds_read_b128 v[222:225], v248 offset:96
	s_cmpk_eq_i32 s14, 0xfe
	s_cbranch_scc1 .Lgq_noload
	global_load_dwordx4 v[160:163], v[206:207], off
	global_load_dwordx4 v[164:167], v[208:209], off

.Lgq_norescale:
	v_add_f32_e32 v245, v245, v226
	v_add_f32_e32 v233, v233, v228
	s_add_i32 s14, s14, 2
	s_cmpk_eq_i32 s14, 0x100
	s_cbranch_scc1 .Lgq_last
	s_and_b32 s12, s14, 2
	s_mulk_i32 s12, 0x2400
	v_add_u32_e32 v250, s12, v243
	s_waitcnt vmcnt(1)
	ds_write_b128 v250, v[160:163]
	s_waitcnt vmcnt(0)
	ds_write_b128 v250, v[164:167] offset:9216
	v_add3_u32 v248, s12, v200, v244
	v_add3_u32 v249, s12, v242, v200
	s_waitcnt lgkmcnt(0)
	s_barrier
	s_branch .Lgq_rot

.Ldf_body:
	ds_read_b128 v[166:169], v246
	ds_read_b128 v[170:173], v246 offset:32
	ds_read_b128 v[174:177], v246 offset:64
	ds_read_b128 v[178:181], v246 offset:96
	ds_read_b128 v[182:185], v246 offset:4608
	ds_read_b128 v[186:189], v246 offset:4640
	ds_read_b128 v[190:193], v246 offset:4672
	ds_read_b128 v[194:197], v246 offset:4704
	s_cmpk_eq_i32 s14, 0x7f
	s_cbranch_scc1 .Ldf_noload
	v_lshl_add_u64 v[248:249], v[148:149], 0, v[200:201]
	v_add_co_u32_e32 v248, vcc, 0xad40000, v248
	v_lshl_add_u64 v[250:251], v[150:151], 0, v[200:201]
	s_nop 0
	v_addc_co_u32_e32 v249, vcc, 0, v249, vcc
	global_load_dwordx4 v[112:115], v[248:249], off offset:1024
	global_load_dwordx4 v[116:119], v[248:249], off offset:1152
	v_add_co_u32_e32 v248, vcc, 0x12d00000, v250
	s_nop 1
	v_addc_co_u32_e32 v249, vcc, 0, v251, vcc
	v_add_co_u32_e32 v250, vcc, 0x12e00000, v250
	s_nop 1
	v_addc_co_u32_e32 v251, vcc, 0, v251, vcc
	global_load_dwordx4 v[136:139], v[248:249], off offset:128
	global_load_dwordx4 v[140:143], v[250:251], off offset:128

.Ldf_norescale:
	v_add_f32_e32 v164, v164, v242
	s_add_i32 s14, s14, 1
	s_cmpk_eq_i32 s14, 0x80
	s_cbranch_scc1 .Ldf_last
	s_bitcmp1_b32 s14, 0
	s_cselect_b32 s12, 0x9000, 0
	v_add_u32_e32 v156, s12, v162
	s_waitcnt vmcnt(3)
	ds_write_b128 v156, v[112:115]
	s_waitcnt vmcnt(2)
	ds_write_b128 v156, v[116:119] offset:9216
	s_waitcnt vmcnt(1)
	ds_write_b128 v156, v[136:139] offset:18432
	s_waitcnt vmcnt(0)
	ds_write_b128 v156, v[140:143] offset:27648
	s_mov_b32 s37, s12
	s_mul_i32 s12, s36, 0x2400
	s_add_i32 s12, s37, s12
	v_add3_u32 v246, s12, v144, v163
	v_add3_u32 v247, s37, v161, v144
	s_waitcnt lgkmcnt(0)
	s_barrier
	s_branch .Ldf_body
